# grid barrier poll loop: s_sleep removed (tighter polling of the 16 XCD generation words)
# speedup vs baseline: 1.0082x; 1.0082x over previous
.LBB0_171:
	global_load_dwordx4 v[6:9], v[0:1], off sc1
	global_load_dwordx4 v[10:13], v[0:1], off offset:16 sc1
	global_load_dwordx4 v[14:17], v[0:1], off offset:32 sc1
	global_load_dwordx4 v[18:21], v[0:1], off offset:48 sc1
	s_waitcnt vmcnt(0)
	s_or_b64 s[10:11], s[10:11], exec
	v_sub_u32_e32 v9, v9, v3
	v_sub_u32_e32 v5, v6, v3
	v_lshrrev_b32_e32 v9, 28, v9
	v_sub_u32_e32 v13, v13, v3
	v_sub_u32_e32 v17, v17, v3
	v_sub_u32_e32 v6, v10, v3
	v_sub_u32_e32 v10, v14, v3
	v_lshrrev_b32_e32 v5, 31, v5
	v_sub_u32_e32 v14, v18, v3
	v_sub_u32_e32 v18, v19, v3
	v_sub_u32_e32 v8, v8, v3
	v_sub_u32_e32 v12, v12, v3
	v_sub_u32_e32 v19, v20, v3
	v_and_b32_e32 v9, 8, v9
	v_and_b32_sdwa v13, v13, s21 dst_sel:DWORD dst_unused:UNUSED_PAD src0_sel:BYTE_3 src1_sel:DWORD
	v_lshrrev_b32_e32 v17, 20, v17
	v_sub_u32_e32 v20, v21, v3
	v_lshrrev_b32_e32 v8, 29, v8
	v_lshrrev_b32_e32 v12, 25, v12
	v_sub_u32_e32 v16, v16, v3
	v_and_b32_e32 v17, 0x800, v17
	v_and_b32_sdwa v20, v20, s22 dst_sel:DWORD dst_unused:UNUSED_PAD src0_sel:WORD_1 src1_sel:DWORD
	v_or3_b32 v5, v13, v5, v9
	v_sub_u32_e32 v7, v7, v3
	v_sub_u32_e32 v11, v11, v3
	v_and_b32_e32 v8, 4, v8
	v_and_b32_e32 v12, 64, v12
	v_lshrrev_b32_e32 v16, 21, v16
	v_lshrrev_b32_e32 v19, 17, v19
	v_or3_b32 v5, v5, v17, v20
	v_lshrrev_b32_e32 v7, 30, v7
	v_lshrrev_b32_e32 v11, 26, v11
	v_sub_u32_e32 v15, v15, v3
	v_and_b32_e32 v16, 0x400, v16
	v_and_b32_e32 v19, 0x4000, v19
	v_or3_b32 v5, v5, v12, v8
	v_and_b32_e32 v7, 2, v7
	v_and_b32_e32 v11, 32, v11
	v_lshrrev_b32_e32 v15, 22, v15
	v_lshrrev_b32_e32 v18, 18, v18
	v_or3_b32 v5, v5, v16, v19
	v_lshrrev_b32_e32 v6, 27, v6
	v_lshrrev_b32_e32 v10, 23, v10
	v_and_b32_e32 v15, 0x200, v15
	v_and_b32_e32 v18, 0x2000, v18
	v_or3_b32 v5, v5, v11, v7
	v_and_b32_e32 v6, 16, v6
	v_and_b32_e32 v10, 0x100, v10
	v_lshrrev_b32_e32 v14, 19, v14
	v_or3_b32 v5, v5, v15, v18
	v_and_b32_e32 v14, 0x1000, v14
	v_or3_b32 v5, v5, v6, v10
	s_waitcnt lgkmcnt(0)
	v_bitop3_b32 v5, v5, v2, v14 bitop3:0xc8
	v_cmp_ne_u32_e32 vcc, 0, v5
	s_or_b64 s[8:9], s[8:9], exec
	s_and_saveexec_b64 s[12:13], vcc
	s_cbranch_execz .LBB0_170
	s_and_b32 s16, s20, 0xff
	s_mov_b64 s[14:15], -1
	s_cmp_eq_u32 s16, 0
	s_mov_b64 s[16:17], -1
	s_mov_b64 s[18:19], -1
	s_cbranch_scc1 .LBB0_175
	s_and_b64 vcc, exec, s[18:19]
	s_cbranch_vccz .LBB0_169

.LBB0_2347:
	global_load_dwordx4 v[6:9], v[0:1], off sc1
	global_load_dwordx4 v[10:13], v[0:1], off offset:16 sc1
	global_load_dwordx4 v[14:17], v[0:1], off offset:32 sc1
	global_load_dwordx4 v[18:21], v[0:1], off offset:48 sc1
	s_waitcnt vmcnt(0)
	s_or_b64 s[8:9], s[8:9], exec
	v_sub_u32_e32 v9, v9, v3
	v_sub_u32_e32 v5, v6, v3
	v_lshrrev_b32_e32 v9, 28, v9
	v_sub_u32_e32 v13, v13, v3
	v_sub_u32_e32 v17, v17, v3
	v_sub_u32_e32 v6, v10, v3
	v_sub_u32_e32 v10, v14, v3
	v_lshrrev_b32_e32 v5, 31, v5
	v_sub_u32_e32 v14, v18, v3
	v_sub_u32_e32 v18, v19, v3
	v_sub_u32_e32 v8, v8, v3
	v_sub_u32_e32 v12, v12, v3
	v_sub_u32_e32 v19, v20, v3
	v_and_b32_e32 v9, 8, v9
	v_and_b32_sdwa v13, v13, s19 dst_sel:DWORD dst_unused:UNUSED_PAD src0_sel:BYTE_3 src1_sel:DWORD
	v_lshrrev_b32_e32 v17, 20, v17
	v_sub_u32_e32 v20, v21, v3
	v_lshrrev_b32_e32 v8, 29, v8
	v_lshrrev_b32_e32 v12, 25, v12
	v_sub_u32_e32 v16, v16, v3
	v_and_b32_e32 v17, 0x800, v17
	v_and_b32_sdwa v20, v20, s20 dst_sel:DWORD dst_unused:UNUSED_PAD src0_sel:WORD_1 src1_sel:DWORD
	v_or3_b32 v5, v13, v5, v9
	v_sub_u32_e32 v7, v7, v3
	v_sub_u32_e32 v11, v11, v3
	v_and_b32_e32 v8, 4, v8
	v_and_b32_e32 v12, 64, v12
	v_lshrrev_b32_e32 v16, 21, v16
	v_lshrrev_b32_e32 v19, 17, v19
	v_or3_b32 v5, v5, v17, v20
	v_lshrrev_b32_e32 v7, 30, v7
	v_lshrrev_b32_e32 v11, 26, v11
	v_sub_u32_e32 v15, v15, v3
	v_and_b32_e32 v16, 0x400, v16
	v_and_b32_e32 v19, 0x4000, v19
	v_or3_b32 v5, v5, v12, v8
	v_and_b32_e32 v7, 2, v7
	v_and_b32_e32 v11, 32, v11
	v_lshrrev_b32_e32 v15, 22, v15
	v_lshrrev_b32_e32 v18, 18, v18
	v_or3_b32 v5, v5, v16, v19
	v_lshrrev_b32_e32 v6, 27, v6
	v_lshrrev_b32_e32 v10, 23, v10
	v_and_b32_e32 v15, 0x200, v15
	v_and_b32_e32 v18, 0x2000, v18
	v_or3_b32 v5, v5, v11, v7
	v_and_b32_e32 v6, 16, v6
	v_and_b32_e32 v10, 0x100, v10
	v_lshrrev_b32_e32 v14, 19, v14
	v_or3_b32 v5, v5, v15, v18
	v_and_b32_e32 v14, 0x1000, v14
	v_or3_b32 v5, v5, v6, v10
	s_waitcnt lgkmcnt(0)
	v_bitop3_b32 v5, v5, v2, v14 bitop3:0xc8
	v_cmp_ne_u32_e32 vcc, 0, v5
	s_or_b64 s[6:7], s[6:7], exec
	s_and_saveexec_b64 s[10:11], vcc
	s_cbranch_execz .LBB0_2346
	s_and_b32 s14, s18, 0xff
	s_mov_b64 s[12:13], -1
	s_cmp_eq_u32 s14, 0
	s_mov_b64 s[14:15], -1
	s_mov_b64 s[16:17], -1
	s_cbranch_scc1 .LBB0_2351
	s_and_b64 vcc, exec, s[16:17]
	s_cbranch_vccz .LBB0_2345
